# GEMM prologues: second K-tile's loads issued with the first (one wait vmcnt(6) retires K-tile 0), barrier count unchanged
# baseline (speedup 1.0000x reference)
.LBB0_199:
	s_add_u32 s76, s50, 0x4000000
	s_addc_u32 s77, s51, 0
	s_add_u32 s68, s50, 0x300000
	s_addc_u32 s69, s51, 0
	s_add_u32 s70, s50, 0x340000
	s_mov_b64 s[78:79], 0x80
	s_addc_u32 s71, s51, 0
	s_add_i32 m0, s34, 0x18000
	v_lshl_add_u64 v[8:9], v[8:9], 0, s[78:79]
	global_load_lds_dwordx4 v[8:9], off
	v_lshl_add_u64 v[4:5], v[4:5], 0, s[78:79]
	s_add_i32 m0, s34, 0x1a000
	s_add_i32 s86, s34, 0x8000
	global_load_lds_dwordx4 v[4:5], off
	v_lshl_add_u64 v[4:5], v[6:7], 0, s[78:79]
	s_mov_b32 m0, s86
	s_add_i32 s87, s34, 0xa000
	global_load_lds_dwordx4 v[4:5], off
	v_lshl_add_u64 v[4:5], v[10:11], 0, s[78:79]
	s_mov_b32 m0, s87
	v_lshl_add_u64 v[2:3], v[2:3], 0, s[78:79]
	global_load_lds_dwordx4 v[4:5], off
	s_add_i32 m0, s34, 0x1c000
	v_lshl_add_u64 v[0:1], v[0:1], 0, s[78:79]
	global_load_lds_dwordx4 v[2:3], off
	s_add_i32 m0, s34, 0x1e000
	s_lshr_b32 s3, s3, 26
	global_load_lds_dwordx4 v[0:1], off
	v_lshrrev_b32_e32 v1, 1, v12
	v_and_b32_e32 v1, 24, v1
	v_and_b32_e32 v0, 15, v12
	s_add_i32 s3, s2, s3
	v_lshlrev_b32_e32 v2, 1, v1
	v_lshlrev_b32_e32 v3, 2, v12
	s_ashr_i32 s33, s3, 6
	v_lshl_or_b32 v2, v0, 6, v2
	s_lshl_b32 s3, s63, 13
	v_and_b32_e32 v3, 32, v3
	v_bitop3_b32 v4, v2, s3, v3 bitop3:0xde
	s_lshl_b32 s3, s5, 5
	s_and_b32 s3, s3, 0x60
	s_lshl_b32 s5, s3, 7
	s_cmp_gt_i32 s2, 63
	s_cselect_b64 s[6:7], -1, 0
	s_add_i32 s90, s33, -2
	v_lshl_or_b32 v184, s63, 6, v0
	v_writelane_b32 v254, s6, 25
	s_cmpk_lt_u32 s4, 0x100
	v_or_b32_e32 v186, s3, v1
	v_cmp_eq_u32_e64 s[2:3], 0, v0
	v_add_u32_e32 v0, v15, v13
	v_bitop3_b32 v185, s5, v2, v3 bitop3:0xf6
	s_waitcnt vmcnt(6)
	s_barrier
	v_writelane_b32 v254, s7, 26
	s_cselect_b64 s[4:5], -1, 0
	v_add_lshl_u32 v136, v0, v14, 1
	v_add_u32_e32 v0, v18, v16
	v_writelane_b32 v254, s4, 27
	v_lshl_add_u64 v[138:139], s[66:67], 0, v[136:137]
	v_add_lshl_u32 v136, v0, v17, 1
	s_add_i32 s89, 0, 0x10000
	s_add_i32 s62, 0, 0x14000
	v_mbcnt_lo_u32_b32 v0, -1, 0
	v_writelane_b32 v254, s5, 28
	s_ashr_i32 s91, s97, 31
	s_ashr_i32 s88, s64, 31
	v_lshl_add_u64 v[140:141], s[66:67], 0, v[136:137]
	v_mov_b64_e32 v[142:143], 0x44
	v_mov_b64_e32 v[144:145], 0x43
	v_add_u32_e32 v187, s89, v185
	v_add_u32_e32 v188, s62, v185
	v_add_u32_e32 v189, 0, v4
	s_movk_i32 s84, 0x1ff
	v_mov_b32_e32 v190, 0xc0447cbd
	s_movk_i32 s85, 0x7fff
	v_mbcnt_hi_u32_b32 v191, -1, v0
	s_barrier
	s_branch .LBB0_202

.LBB0_1256:
	v_lshrrev_b32_e32 v10, 1, v8
	v_and_b32_e32 v10, 24, v10
	s_sext_i32_i8 s86, s2
	s_add_u32 s2, s50, 0x2b00000
	v_and_b32_e32 v9, 15, v8
	v_lshlrev_b32_e32 v11, 1, v10
	v_lshlrev_b32_e32 v8, 2, v8
	s_addc_u32 s3, s51, 0
	v_lshl_or_b32 v136, s4, 6, v9
	v_lshl_or_b32 v9, v9, 6, v11
	s_lshl_b32 s4, s4, 13
	v_and_b32_e32 v8, 32, v8
	v_bitop3_b32 v11, v9, s4, v8 bitop3:0xde
	s_lshl_b32 s4, s5, 5
	s_and_b32 s12, s4, 0x60
	s_lshl_b32 s4, s12, 7
	v_bitop3_b32 v137, s4, v9, v8 bitop3:0xf6
	s_mov_b64 s[4:5], 0x80
	s_add_i32 m0, s23, 0x18000
	v_lshl_add_u64 v[6:7], v[6:7], 0, s[4:5]
	global_load_lds_dwordx4 v[6:7], off
	v_lshl_add_u64 v[4:5], v[4:5], 0, s[4:5]
	s_add_i32 m0, s23, 0x1a000
	s_add_i32 s81, s23, 0x8000
	s_add_i32 s82, s23, 0xa000
	global_load_lds_dwordx4 v[4:5], off
	v_lshl_add_u64 v[0:1], v[0:1], 0, s[4:5]
	s_mov_b32 m0, s81
	s_add_u32 s10, s74, 0x40080
	global_load_lds_dwordx4 v[0:1], off
	v_lshl_add_u64 v[0:1], v[2:3], 0, s[4:5]
	s_mov_b32 m0, s82
	s_addc_u32 s11, s75, 0
	global_load_lds_dwordx4 v[0:1], off
	s_add_i32 m0, s23, 0x1c000
	v_lshl_add_u64 v[0:1], s[10:11], 0, v[130:131]
	global_load_lds_dwordx4 v[0:1], off
	v_lshl_add_u64 v[0:1], s[10:11], 0, v[134:135]
	s_add_i32 m0, s23, 0x1e000
	s_cmpk_lt_u32 s6, 0x100
	global_load_lds_dwordx4 v[0:1], off
	s_cselect_b64 s[6:7], -1, 0
	s_ashr_i32 s83, s97, 31
	s_waitcnt vmcnt(6)
	s_barrier
	s_add_u32 s8, s8, s97
	s_addc_u32 s9, s9, s83
	s_add_i32 s84, 0, 0x10000
	s_add_i32 s85, 0, 0x14000
	v_or_b32_e32 v138, s12, v10
	v_add_u32_e32 v139, s84, v137
	v_add_u32_e32 v140, s85, v137
	v_add_u32_e32 v141, 0, v11
	s_mov_b64 s[10:11], 0x100
	s_mov_b64 s[12:13], 0x180
	s_barrier
	s_branch .LBB0_1259

.LBB0_1383:
	s_add_u32 s16, s50, 0x9800000
	v_bfe_u32 v16, v8, 4, 2
	s_mov_b64 s[18:19], 0x80
	s_addc_u32 s17, s51, 0
	s_and_b32 s10, s2, 3
	v_and_b32_e32 v15, 15, v8
	s_mul_i32 s2, s3, 48
	v_lshlrev_b32_e32 v18, 4, v16
	v_lshlrev_b32_e32 v8, 2, v8
	s_add_i32 m0, s25, 0x18000
	v_lshl_add_u64 v[6:7], v[6:7], 0, s[18:19]
	v_or_b32_e32 v115, s2, v15
	v_lshl_or_b32 v15, v15, 6, v18
	v_and_b32_e32 v8, 32, v8
	s_lshl_b32 s2, s10, 12
	global_load_lds_dwordx4 v[6:7], off
	v_lshl_add_u64 v[4:5], v[4:5], 0, s[18:19]
	s_add_i32 m0, s25, 0x1a000
	s_add_i32 s75, s25, 0x8000
	s_add_i32 s76, s25, 0xa000
	s_mulk_i32 s3, 0x1800
	v_bitop3_b32 v142, s2, v15, v8 bitop3:0xf6
	global_load_lds_dwordx4 v[4:5], off
	v_lshl_add_u64 v[0:1], v[0:1], 0, s[18:19]
	s_mov_b32 m0, s75
	s_add_u32 s2, s12, 0x40080
	v_bitop3_b32 v18, v15, s3, v8 bitop3:0xde
	global_load_lds_dwordx4 v[0:1], off
	v_lshl_add_u64 v[0:1], v[2:3], 0, s[18:19]
	s_mov_b32 m0, s76
	s_addc_u32 s3, s13, 0
	global_load_lds_dwordx4 v[0:1], off
	s_add_i32 m0, s25, 0x1c000
	v_lshl_add_u64 v[0:1], s[2:3], 0, v[106:107]
	global_load_lds_dwordx4 v[0:1], off
	v_lshl_add_u64 v[0:1], s[2:3], 0, v[110:111]
	s_add_i32 m0, s25, 0x1e000
	v_lshlrev_b32_e32 v17, 3, v16
	global_load_lds_dwordx4 v[0:1], off
	v_and_b32_e32 v0, 8, v17
	v_cvt_f32_ubyte0_e32 v1, v0
	v_mul_f32_e32 v1, 0xbf549a78, v1
	v_exp_f32_e32 v144, v1
	v_or_b32_e32 v1, 1, v0
	v_cvt_f32_ubyte0_e32 v1, v1
	v_mul_f32_e32 v1, 0xbf549a78, v1
	v_exp_f32_e32 v145, v1
	v_or_b32_e32 v1, 2, v0
	v_cvt_f32_ubyte0_e32 v1, v1
	v_mul_f32_e32 v1, 0xbf549a78, v1
	v_exp_f32_e32 v146, v1
	v_or_b32_e32 v1, 3, v0
	v_cvt_f32_ubyte0_e32 v1, v1
	v_mul_f32_e32 v1, 0xbf549a78, v1
	v_exp_f32_e32 v147, v1
	v_or_b32_e32 v1, 4, v0
	v_cvt_f32_ubyte0_e32 v1, v1
	v_mul_f32_e32 v1, 0xbf549a78, v1
	v_exp_f32_e32 v148, v1
	v_or_b32_e32 v1, 5, v0
	v_cvt_f32_ubyte0_e32 v1, v1
	v_mul_f32_e32 v1, 0xbf549a78, v1
	v_exp_f32_e32 v149, v1
	v_or_b32_e32 v1, 6, v0
	v_or_b32_e32 v0, 7, v0
	s_cmpk_lt_u32 s6, 0x100
	v_lshl_or_b32 v114, s10, 5, v17
	v_cvt_f32_ubyte0_e32 v1, v1
	v_cvt_f32_ubyte0_e32 v0, v0
	s_cselect_b64 s[20:21], -1, 0
	s_cmp_eq_u32 s10, 0
	v_mul_f32_e32 v1, 0xbf549a78, v1
	v_mul_f32_e32 v0, 0xbf549a78, v0
	v_lshlrev_b32_e32 v112, 1, v114
	s_cselect_b64 s[6:7], -1, 0
	s_cmp_lt_u32 s10, 2
	v_exp_f32_e32 v150, v1
	v_exp_f32_e32 v151, v0
	v_lshl_add_u64 v[0:1], s[50:51], 0, v[112:113]
	s_mov_b64 s[8:9], 0xda00000
	v_add_u32_e32 v143, 0x60, v115
	s_cselect_b64 s[22:23], -1, 0
	v_lshl_add_u64 v[116:117], v[0:1], 0, s[8:9]
	s_add_i32 s8, 0, 0x20000
	v_lshl_add_u32 v156, v115, 4, s8
	s_lshl_b32 s9, s10, 2
	v_lshl_add_u32 v158, v143, 4, s8
	v_lshlrev_b32_e32 v112, 2, v114
	s_add_i32 s8, 0, 0x21400
	v_add_u32_e32 v157, s9, v156
	v_add_u32_e32 v159, s9, v158
	v_add_u32_e32 v160, s8, v112
	v_lshl_add_u64 v[2:3], s[48:49], 0, v[112:113]
	s_mov_b64 s[8:9], 0x3000000
	v_lshl_add_u64 v[118:119], v[2:3], 0, s[8:9]
	s_mov_b64 s[8:9], 0x3200000
	v_lshl_add_u64 v[120:121], v[2:3], 0, s[8:9]
	s_add_i32 s8, 0, 0x21000
	v_add_u32_e32 v161, s8, v112
	s_mov_b64 s[8:9], 0xd400000
	v_lshl_add_u64 v[122:123], v[0:1], 0, s[8:9]
	v_lshlrev_b32_e32 v0, 14, v9
	v_and_b32_e32 v0, 0xffff8000, v0
	v_lshl_add_u32 v0, v10, 11, v0
	v_and_b32_e32 v1, 1, v9
	v_lshl_or_b32 v0, v1, 6, v0
	v_lshl_add_u32 v124, v11, 1, v0
	v_lshlrev_b32_e32 v0, 14, v12
	v_and_b32_e32 v0, 0xffff8000, v0
	v_add_u32_e32 v152, 16, v115
	v_lshl_add_u32 v0, v13, 11, v0
	v_and_b32_e32 v1, 1, v12
	v_lshlrev_b32_e32 v4, 4, v152
	v_add_u32_e32 v153, 32, v115
	v_lshl_or_b32 v0, v1, 6, v0
	v_lshlrev_b32_e32 v5, 4, v153
	v_add_u32_e32 v154, 0x70, v115
	v_lshl_add_u32 v126, v14, 1, v0
	v_add_u32_e32 v0, 0, v4
	v_lshlrev_b32_e32 v6, 4, v154
	v_add_u32_e32 v155, 0x80, v115
	v_add_u32_e32 v165, 0x20000, v0
	v_add_u32_e32 v0, 0, v5
	v_lshlrev_b32_e32 v7, 4, v155
	v_add_u32_e32 v166, 0x20000, v0
	v_add_u32_e32 v0, 0, v6
	s_waitcnt vmcnt(6)
	s_barrier
	v_add_u32_e32 v167, 0x20000, v0
	v_add_u32_e32 v0, 0, v7
	v_add_u32_e32 v168, 0x20000, v0
	v_mbcnt_lo_u32_b32 v0, -1, 0
	v_cmp_eq_u32_e64 s[2:3], 0, v16
	v_cmp_gt_u32_e64 s[4:5], 2, v16
	s_ashr_i32 s77, s97, 31
	s_ashr_i32 s78, s96, 31
	v_add_u32_e32 v162, 0x200, v161
	v_mov_b32_e32 v125, v113
	v_mov_b32_e32 v127, v113
	s_add_i32 s79, 0, 0x10000
	s_add_i32 s80, 0, 0x14000
	v_add_u32_e32 v163, 0, v18
	s_movk_i32 s81, 0xfff
	s_movk_i32 s82, 0x1000
	v_mov_b32_e32 v164, 0x358637bd
	s_movk_i32 s83, 0x180
	s_movk_i32 s84, 0xc00
	v_mov_b64_e32 v[128:129], 0x200
	v_mov_b64_e32 v[130:131], 0x1ff
	v_mbcnt_hi_u32_b32 v169, -1, v0
	s_barrier
	s_branch .LBB0_1386

.LBB0_1764:
	s_add_u32 s12, s50, 0xe100000
	s_mov_b64 s[14:15], 0x80
	s_addc_u32 s13, s51, 0
	s_add_i32 m0, s62, 0x18000
	v_lshl_add_u64 v[8:9], v[8:9], 0, s[14:15]
	global_load_lds_dwordx4 v[8:9], off
	v_lshl_add_u64 v[4:5], v[4:5], 0, s[14:15]
	s_add_i32 m0, s62, 0x1a000
	s_add_i32 s67, s62, 0x8000
	global_load_lds_dwordx4 v[4:5], off
	v_lshl_add_u64 v[4:5], v[6:7], 0, s[14:15]
	s_mov_b32 m0, s67
	s_add_i32 s72, s62, 0xa000
	global_load_lds_dwordx4 v[4:5], off
	v_lshl_add_u64 v[4:5], v[10:11], 0, s[14:15]
	s_mov_b32 m0, s72
	v_lshl_add_u64 v[2:3], v[2:3], 0, s[14:15]
	global_load_lds_dwordx4 v[4:5], off
	s_add_i32 m0, s62, 0x1c000
	v_lshl_add_u64 v[0:1], v[0:1], 0, s[14:15]
	global_load_lds_dwordx4 v[2:3], off
	s_add_i32 m0, s62, 0x1e000
	s_lshr_b32 s3, s3, 26
	global_load_lds_dwordx4 v[0:1], off
	v_lshrrev_b32_e32 v1, 1, v189
	v_and_b32_e32 v1, 24, v1
	v_and_b32_e32 v0, 15, v189
	s_add_i32 s3, s2, s3
	v_lshlrev_b32_e32 v2, 1, v1
	s_ashr_i32 s73, s3, 6
	v_lshl_or_b32 v146, s5, 6, v0
	v_lshl_or_b32 v0, v0, 6, v2
	s_lshl_b32 s3, s5, 13
	v_and_b32_e32 v2, 32, v190
	v_bitop3_b32 v3, v0, s3, v2 bitop3:0xde
	s_lshl_b32 s3, s4, 5
	s_and_b32 s4, s3, 0x60
	s_lshl_b32 s3, s4, 7
	v_bitop3_b32 v147, s3, v0, v2 bitop3:0xf6
	s_cmp_gt_i32 s2, 63
	v_add_u32_e32 v0, v14, v12
	s_cselect_b64 s[2:3], -1, 0
	s_cmpk_lt_i32 s96, 0x70
	v_or_b32_e32 v148, s4, v1
	v_add_lshl_u32 v0, v0, v13, 1
	v_mov_b32_e32 v1, v131
	s_cselect_b64 s[16:17], -1, 0
	s_add_i32 s74, s96, 0xe8
	s_add_i32 s75, s73, -2
	v_lshl_add_u64 v[136:137], s[6:7], 0, v[0:1]
	v_add_u32_e32 v0, v17, v15
	s_waitcnt vmcnt(6)
	s_barrier
	s_cmpk_lt_u32 s18, 0x100
	v_add_lshl_u32 v0, v0, v16, 1
	s_cselect_b64 s[18:19], -1, 0
	v_lshl_add_u64 v[138:139], s[6:7], 0, v[0:1]
	v_cndmask_b32_e64 v0, 0, 1, s[2:3]
	s_add_i32 s76, 0, 0x10000
	s_add_i32 s77, 0, 0x14000
	v_add_u32_e32 v149, s76, v147
	v_add_u32_e32 v150, s77, v147
	v_add_u32_e32 v151, 0, v3
	s_movk_i32 s78, 0x180
	s_movk_i32 s79, 0x600
	v_cmp_ne_u32_e64 s[2:3], 1, v0
	s_barrier
	s_branch .LBB0_1767

.LBB0_2283:
	s_add_u32 s83, s50, 0x102000
	s_addc_u32 s84, s51, 0
	s_add_u32 s20, s50, 0x128000
	s_addc_u32 s21, s51, 0
	s_add_u32 s22, s50, 0x170000
	s_mov_b64 s[24:25], 0x80
	s_addc_u32 s23, s51, 0
	s_and_b32 s14, s2, 3
	s_add_i32 m0, s35, 0x18000
	v_lshl_add_u64 v[6:7], v[6:7], 0, s[24:25]
	s_lshl_b32 s5, s14, 12
	global_load_lds_dwordx4 v[6:7], off
	v_lshl_add_u64 v[4:5], v[4:5], 0, s[24:25]
	s_add_i32 m0, s35, 0x1a000
	s_add_i32 s86, s35, 0x8000
	s_add_i32 s87, s35, 0xa000
	global_load_lds_dwordx4 v[4:5], off
	v_lshl_add_u64 v[2:3], v[2:3], 0, s[24:25]
	s_mov_b32 m0, s86
	s_add_u32 s2, s6, 0x40080
	global_load_lds_dwordx4 v[2:3], off
	v_lshl_add_u64 v[0:1], v[0:1], 0, s[24:25]
	s_mov_b32 m0, s87
	s_addc_u32 s3, s7, 0
	global_load_lds_dwordx4 v[0:1], off
	s_add_i32 m0, s35, 0x1c000
	v_lshl_add_u64 v[0:1], s[2:3], 0, v[110:111]
	global_load_lds_dwordx4 v[0:1], off
	v_lshl_add_u64 v[0:1], s[2:3], 0, v[114:115]
	s_add_i32 m0, s35, 0x1e000
	s_mul_i32 s2, s33, 0x1800
	global_load_lds_dwordx4 v[0:1], off
	v_and_b32_e32 v0, 15, v8
	v_and_b32_e32 v1, 48, v8
	v_lshl_or_b32 v0, v0, 6, v1
	v_lshlrev_b32_e32 v1, 2, v8
	v_and_b32_e32 v1, 32, v1
	v_bitop3_b32 v2, v0, s2, v1 bitop3:0xde
	v_bitop3_b32 v220, s5, v0, v1 bitop3:0xf6
	v_lshlrev_b32_e32 v0, 14, v9
	v_and_b32_e32 v0, 0xffff8000, v0
	v_lshl_add_u32 v0, v10, 11, v0
	v_and_b32_e32 v1, 1, v9
	v_lshl_or_b32 v0, v1, 6, v0
	v_lshl_add_u32 v118, v11, 1, v0
	v_lshlrev_b32_e32 v0, 14, v12
	v_and_b32_e32 v0, 0xffff8000, v0
	s_waitcnt vmcnt(6)
	s_barrier
	s_cmpk_lt_u32 s4, 0x100
	v_lshl_add_u32 v0, v13, 11, v0
	v_and_b32_e32 v1, 1, v12
	s_cselect_b64 s[18:19], -1, 0
	v_lshl_or_b32 v0, v1, 6, v0
	s_add_i32 s90, 0, 0x10000
	s_add_i32 s91, 0, 0x14000
	s_ashr_i32 s88, s97, 31
	s_ashr_i32 s89, s96, 31
	v_mov_b32_e32 v119, v116
	v_lshl_add_u32 v120, v14, 1, v0
	v_mov_b32_e32 v121, v116
	v_mov_b64_e32 v[122:123], 0x100
	v_mov_b64_e32 v[124:125], 0xff
	v_add_u32_e32 v221, s90, v220
	v_add_u32_e32 v222, s91, v220
	v_add_u32_e32 v223, 0, v2
	s_mov_b32 s52, 0x3fb504f3
	v_mov_b32_e32 v3, 1.0
	s_mov_b64 s[54:55], 0x3000
	s_mov_b64 s[56:57], 0x4000
	v_mov_b32_e32 v224, 0xc0
	v_mov_b32_e32 v225, 0x1800
	s_mov_b32 s92, 0
	s_barrier
	s_branch .LBB0_2286

.LBB0_2364:
	v_readlane_b32 s68, v254, 3
	v_readlane_b32 s76, v254, 11
	v_readlane_b32 s77, v254, 12
	v_readlane_b32 s78, v254, 13
	v_readlane_b32 s79, v254, 14
	v_readlane_b32 s80, v254, 15
	v_readlane_b32 s81, v254, 16
	v_readlane_b32 s82, v254, 17
	v_readlane_b32 s83, v254, 18
	s_mov_b64 s[44:45], s[76:77]
	s_mov_b64 s[50:51], s[82:83]
	s_add_u32 s6, s50, 0x9800000
	s_addc_u32 s7, s51, 0
	s_lshl_b32 s8, s8, 5
	s_and_b32 s14, s8, 0x60
	s_mov_b64 s[8:9], 0x80
	s_add_i32 m0, s43, 0x18000
	v_lshl_add_u64 v[6:7], v[6:7], 0, s[8:9]
	s_lshl_b32 s11, s10, 13
	s_lshl_b32 s15, s14, 7
	global_load_lds_dwordx4 v[6:7], off
	v_lshl_add_u64 v[4:5], v[4:5], 0, s[8:9]
	s_add_i32 m0, s43, 0x1a000
	s_add_i32 s67, s43, 0x8000
	s_add_i32 s68, s43, 0xa000
	global_load_lds_dwordx4 v[4:5], off
	v_lshl_add_u64 v[0:1], v[0:1], 0, s[8:9]
	s_mov_b32 m0, s67
	s_add_u32 s12, s54, 0x40080
	global_load_lds_dwordx4 v[0:1], off
	v_lshl_add_u64 v[0:1], v[2:3], 0, s[8:9]
	s_mov_b32 m0, s68
	s_addc_u32 s13, s55, 0
	global_load_lds_dwordx4 v[0:1], off
	s_add_i32 m0, s43, 0x1c000
	v_lshl_add_u64 v[0:1], s[12:13], 0, v[132:133]
	global_load_lds_dwordx4 v[0:1], off
	v_lshl_add_u64 v[0:1], s[12:13], 0, v[128:129]
	s_add_i32 m0, s43, 0x1e000
	v_readlane_b32 s70, v254, 5
	global_load_lds_dwordx4 v[0:1], off
	v_lshrrev_b32_e32 v1, 1, v9
	v_and_b32_e32 v1, 24, v1
	v_and_b32_e32 v0, 15, v9
	v_lshlrev_b32_e32 v2, 1, v1
	v_lshl_or_b32 v144, s10, 6, v0
	v_lshl_or_b32 v0, v0, 6, v2
	v_lshlrev_b32_e32 v2, 2, v9
	v_and_b32_e32 v2, 32, v2
	v_bitop3_b32 v3, v0, s11, v2 bitop3:0xde
	v_bitop3_b32 v145, s15, v0, v2 bitop3:0xf6
	v_lshlrev_b32_e32 v0, 14, v13
	v_and_b32_e32 v0, 0xffff8000, v0
	v_or_b32_e32 v146, s14, v1
	v_lshl_add_u32 v0, v12, 11, v0
	v_and_b32_e32 v1, 1, v13
	v_lshl_or_b32 v0, v1, 6, v0
	v_lshl_add_u32 v136, v14, 1, v0
	v_lshlrev_b32_e32 v0, 14, v8
	v_and_b32_e32 v0, 0xffff8000, v0
	v_readlane_b32 s71, v254, 6
	s_waitcnt vmcnt(6)
	s_barrier
	s_cmpk_lt_u32 s3, 0x100
	v_lshl_add_u32 v0, v10, 11, v0
	v_and_b32_e32 v1, 1, v8
	v_readlane_b32 s69, v254, 4
	v_readlane_b32 s72, v254, 7
	v_readlane_b32 s73, v254, 8
	v_readlane_b32 s74, v254, 9
	v_readlane_b32 s75, v254, 10
	s_cselect_b64 s[10:11], -1, 0
	v_lshl_or_b32 v0, v1, 6, v0
	s_add_i32 s70, 0, 0x10000
	s_add_i32 s71, 0, 0x14000
	s_sext_i32_i8 s75, s2
	s_ashr_i32 s69, s97, 31
	v_mov_b32_e32 v137, v133
	v_lshl_add_u32 v138, v11, 1, v0
	v_mov_b32_e32 v139, v133
	v_mov_b64_e32 v[140:141], 0x300
	v_mov_b64_e32 v[142:143], 0x2ff
	v_add_u32_e32 v147, s70, v145
	v_add_u32_e32 v148, s71, v145
	v_add_u32_e32 v149, 0, v3
	s_mov_b64 s[12:13], 0x120000
	s_mov_b32 s72, 0x120000
	s_mov_b64 s[14:15], 0x140000
	s_mov_b32 s73, 0x140000
	s_mov_b64 s[16:17], 0x160000
	s_mov_b32 s74, 0x160000
	s_mov_b64 s[46:47], s[78:79]
	s_mov_b64 s[48:49], s[80:81]
	s_barrier
	s_branch .LBB0_2367

.LBB0_2436:
	v_readlane_b32 s40, v254, 3
	v_readlane_b32 s48, v254, 11
	v_readlane_b32 s49, v254, 12
	v_readlane_b32 s50, v254, 13
	v_readlane_b32 s51, v254, 14
	v_readlane_b32 s52, v254, 15
	v_readlane_b32 s53, v254, 16
	v_readlane_b32 s54, v254, 17
	v_readlane_b32 s55, v254, 18
	s_mov_b64 s[24:25], s[48:49]
	s_mov_b64 s[30:31], s[54:55]
	s_add_u32 s88, s30, 0x105000
	s_addc_u32 s89, s31, 0
	s_add_u32 s56, s30, 0x128040
	s_addc_u32 s57, s31, 0
	s_add_u32 s90, s30, 0x112000
	s_mov_b64 s[28:29], s[52:53]
	s_addc_u32 s91, s31, 0
	s_add_u32 s28, s30, 0x300000
	s_addc_u32 s29, s31, 0
	s_add_u32 s64, s30, 0x170000
	s_mov_b64 s[66:67], 0x80
	s_addc_u32 s65, s31, 0
	s_and_b32 s92, s2, 3
	s_add_i32 m0, s84, 0x18000
	v_lshl_add_u64 v[4:5], v[4:5], 0, s[66:67]
	s_lshl_b32 s5, s92, 12
	global_load_lds_dwordx4 v[4:5], off
	v_lshl_add_u64 v[2:3], v[2:3], 0, s[66:67]
	s_add_i32 m0, s84, 0x1a000
	s_add_i32 s93, s84, 0x8000
	s_add_i32 s94, s84, 0xa000
	global_load_lds_dwordx4 v[2:3], off
	v_lshl_add_u64 v[0:1], v[0:1], 0, s[66:67]
	s_mov_b32 m0, s93
	s_add_u32 s2, s6, 0x100080
	global_load_lds_dwordx4 v[0:1], off
	v_lshl_add_u64 v[0:1], v[6:7], 0, s[66:67]
	s_mov_b32 m0, s94
	s_addc_u32 s3, s7, 0
	global_load_lds_dwordx4 v[0:1], off
	s_add_i32 m0, s84, 0x1c000
	v_lshl_add_u64 v[0:1], s[2:3], 0, v[110:111]
	global_load_lds_dwordx4 v[0:1], off
	v_lshl_add_u64 v[0:1], s[2:3], 0, v[114:115]
	s_add_i32 m0, s84, 0x1e000
	s_mul_i32 s2, s35, 0x1800
	global_load_lds_dwordx4 v[0:1], off
	v_and_b32_e32 v0, 15, v8
	v_and_b32_e32 v1, 48, v8
	v_lshl_or_b32 v0, v0, 6, v1
	v_lshlrev_b32_e32 v1, 2, v8
	v_and_b32_e32 v1, 32, v1
	v_bitop3_b32 v2, v0, s2, v1 bitop3:0xde
	v_bitop3_b32 v220, s5, v0, v1 bitop3:0xf6
	v_lshlrev_b32_e32 v0, 16, v9
	v_and_b32_e32 v0, 0xfffe0000, v0
	v_lshl_add_u32 v0, v10, 13, v0
	v_and_b32_e32 v1, 1, v9
	v_lshl_or_b32 v0, v1, 6, v0
	v_lshl_add_u32 v118, v11, 1, v0
	v_lshlrev_b32_e32 v0, 16, v12
	s_cmpk_lt_u32 s4, 0x100
	v_and_b32_e32 v0, 0xfffe0000, v0
	s_waitcnt vmcnt(6)
	s_barrier
	s_cselect_b64 s[2:3], -1, 0
	v_lshl_add_u32 v0, v13, 13, v0
	v_and_b32_e32 v1, 1, v12
	s_mov_b64 s[26:27], s[50:51]
	v_writelane_b32 v255, s2, 56
	s_ashr_i32 s95, s97, 31
	v_lshl_or_b32 v0, v1, 6, v0
	s_add_i32 s97, 0, 0x10000
	s_add_i32 s62, 0, 0x14000
	v_writelane_b32 v255, s3, 57
	s_ashr_i32 s96, s96, 31
	v_mov_b32_e32 v119, v116
	v_lshl_add_u32 v120, v14, 1, v0
	v_mov_b32_e32 v121, v116
	v_mov_b64_e32 v[122:123], 0x100
	v_mov_b64_e32 v[124:125], 0xff
	v_add_u32_e32 v221, s97, v220
	v_add_u32_e32 v222, s62, v220
	v_add_u32_e32 v223, 0, v2
	s_mov_b32 s70, 0x3fb504f3
	v_mov_b32_e32 v3, 4.0
	s_movk_i32 s63, 0x68
	s_mov_b64 s[72:73], 0x1000
	s_movk_i32 s38, 0x1000
	s_mov_b32 s39, 0x2aaaaaab
	s_movk_i32 s27, 0x7f8
	v_mov_b32_e32 v224, 0xc0
	v_mov_b32_e32 v225, 0x1800
	s_mov_b32 s33, 0
	v_readlane_b32 s41, v254, 4
	v_readlane_b32 s42, v254, 5
	v_readlane_b32 s43, v254, 6
	v_readlane_b32 s44, v254, 7
	v_readlane_b32 s45, v254, 8
	v_readlane_b32 s46, v254, 9
	v_readlane_b32 s47, v254, 10
	s_barrier
	s_branch .LBB0_2439

.LBB0_2565:
	s_and_b64 s[16:17], s[16:17], exec
	v_and_b32_e32 v8, 48, v136
	v_lshlrev_b32_e32 v9, 6, v136
	s_movk_i32 s17, 0x3c0
	v_and_or_b32 v8, v9, s17, v8
	v_lshlrev_b32_e32 v9, 2, v136
	s_cselect_b32 s34, 14, 18
	s_lshl_b32 s16, s18, 13
	v_and_b32_e32 v9, 32, v9
	v_bitop3_b32 v10, v8, s16, v9 bitop3:0xde
	s_lshl_b32 s16, s1, 5
	s_and_b32 s26, s16, 0x60
	s_lshl_b32 s16, s26, 7
	v_bitop3_b32 v8, s16, v8, v9 bitop3:0xf6
	s_mov_b64 s[16:17], 0x80
	s_add_i32 m0, s24, 0x18000
	v_lshl_add_u64 v[6:7], v[6:7], 0, s[16:17]
	s_lshl_b32 s7, s18, 6
	global_load_lds_dwordx4 v[6:7], off
	v_lshl_add_u64 v[4:5], v[4:5], 0, s[16:17]
	s_add_i32 m0, s24, 0x1a000
	s_add_i32 s35, s24, 0x8000
	s_add_i32 s42, s24, 0xa000
	global_load_lds_dwordx4 v[4:5], off
	v_lshl_add_u64 v[2:3], v[2:3], 0, s[16:17]
	s_mov_b32 m0, s35
	s_add_u32 s18, s4, 0x80080
	global_load_lds_dwordx4 v[2:3], off
	v_lshl_add_u64 v[0:1], v[0:1], 0, s[16:17]
	s_mov_b32 m0, s42
	s_addc_u32 s19, s5, 0
	global_load_lds_dwordx4 v[0:1], off
	s_add_i32 m0, s24, 0x1c000
	v_lshl_add_u64 v[0:1], s[18:19], 0, v[132:133]
	global_load_lds_dwordx4 v[0:1], off
	v_lshl_add_u64 v[0:1], s[18:19], 0, v[128:129]
	s_add_i32 m0, s24, 0x1e000
	s_add_i32 s54, 0, 0x10000
	global_load_lds_dwordx4 v[0:1], off
	s_waitcnt vmcnt(6)
	s_barrier
	s_add_i32 s56, 0, 0x14000
	s_add_i32 s62, 0, 0x18000
	s_add_i32 s64, 0, 0x1c000
	v_add_u32_e32 v137, s54, v8
	v_add_u32_e32 v138, s56, v8
	s_add_i32 s54, s54, s14
	s_add_i32 s56, s56, s14
	v_add_u32_e32 v140, s62, v8
	v_add_u32_e32 v141, s64, v8
	s_add_i32 s62, s62, s14
	s_add_i32 s64, s64, s14
	s_add_i32 s43, s34, -2
	v_add_u32_e32 v139, 0, v10
	s_add_i32 s52, s24, 0xc000
	s_add_i32 s53, s24, 0xe000
	s_add_i32 s55, s54, 0x2000
	s_add_i32 s57, s56, 0x2000
	s_add_i32 s63, s62, 0x2000
	s_add_i32 s65, s64, 0x2000
	s_mov_b32 s18, 0
	v_mov_b32_e32 v0, v133
	v_mov_b32_e32 v1, v133
	v_mov_b32_e32 v2, v133
	v_mov_b32_e32 v3, v133
	v_mov_b32_e32 v4, v133
	v_mov_b32_e32 v5, v133
	v_mov_b32_e32 v6, v133
	v_mov_b32_e32 v7, v133
	v_mov_b32_e32 v8, v133
	v_mov_b32_e32 v9, v133
	v_mov_b32_e32 v10, v133
	v_mov_b32_e32 v11, v133
	v_mov_b32_e32 v12, v133
	v_mov_b32_e32 v13, v133
	v_mov_b32_e32 v14, v133
	v_mov_b32_e32 v15, v133
	v_mov_b32_e32 v16, v133
	v_mov_b32_e32 v17, v133
	v_mov_b32_e32 v18, v133
	v_mov_b32_e32 v19, v133
	v_mov_b32_e32 v20, v133
	v_mov_b32_e32 v21, v133
	v_mov_b32_e32 v22, v133
	v_mov_b32_e32 v23, v133
	v_mov_b32_e32 v24, v133
	v_mov_b32_e32 v25, v133
	v_mov_b32_e32 v26, v133
	v_mov_b32_e32 v27, v133
	v_mov_b32_e32 v28, v133
	v_mov_b32_e32 v29, v133
	v_mov_b32_e32 v30, v133
	v_mov_b32_e32 v31, v133
	v_mov_b32_e32 v32, v133
	v_mov_b32_e32 v33, v133
	v_mov_b32_e32 v34, v133
	v_mov_b32_e32 v35, v133
	v_mov_b32_e32 v36, v133
	v_mov_b32_e32 v37, v133
	v_mov_b32_e32 v38, v133
	v_mov_b32_e32 v39, v133
	v_mov_b32_e32 v40, v133
	v_mov_b32_e32 v41, v133
	v_mov_b32_e32 v42, v133
	v_mov_b32_e32 v43, v133
	v_mov_b32_e32 v44, v133
	v_mov_b32_e32 v45, v133
	v_mov_b32_e32 v46, v133
	v_mov_b32_e32 v47, v133
	v_mov_b32_e32 v48, v133
	v_mov_b32_e32 v49, v133
	v_mov_b32_e32 v50, v133
	v_mov_b32_e32 v51, v133
	v_mov_b32_e32 v52, v133
	v_mov_b32_e32 v53, v133
	v_mov_b32_e32 v54, v133
	v_mov_b32_e32 v55, v133
	v_mov_b32_e32 v56, v133
	v_mov_b32_e32 v57, v133
	v_mov_b32_e32 v58, v133
	v_mov_b32_e32 v59, v133
	v_mov_b32_e32 v60, v133
	v_mov_b32_e32 v61, v133
	v_mov_b32_e32 v62, v133
	v_mov_b32_e32 v63, v133
	v_mov_b32_e32 v64, v133
	v_mov_b32_e32 v65, v133
	v_mov_b32_e32 v66, v133
	v_mov_b32_e32 v67, v133
	v_mov_b32_e32 v68, v133
	v_mov_b32_e32 v69, v133
	v_mov_b32_e32 v70, v133
	v_mov_b32_e32 v71, v133
	v_mov_b32_e32 v72, v133
	v_mov_b32_e32 v73, v133
	v_mov_b32_e32 v74, v133
	v_mov_b32_e32 v75, v133
	v_mov_b32_e32 v76, v133
	v_mov_b32_e32 v77, v133
	v_mov_b32_e32 v78, v133
	v_mov_b32_e32 v79, v133
	v_mov_b32_e32 v80, v133
	v_mov_b32_e32 v81, v133
	v_mov_b32_e32 v82, v133
	v_mov_b32_e32 v83, v133
	v_mov_b32_e32 v84, v133
	v_mov_b32_e32 v85, v133
	v_mov_b32_e32 v86, v133
	v_mov_b32_e32 v87, v133
	v_mov_b32_e32 v88, v133
	v_mov_b32_e32 v89, v133
	v_mov_b32_e32 v90, v133
	v_mov_b32_e32 v91, v133
	v_mov_b32_e32 v92, v133
	v_mov_b32_e32 v93, v133
	v_mov_b32_e32 v94, v133
	v_mov_b32_e32 v95, v133
	v_mov_b32_e32 v96, v133
	v_mov_b32_e32 v97, v133
	v_mov_b32_e32 v98, v133
	v_mov_b32_e32 v99, v133
	v_mov_b32_e32 v100, v133
	v_mov_b32_e32 v101, v133
	v_mov_b32_e32 v102, v133
	v_mov_b32_e32 v103, v133
	v_mov_b32_e32 v104, v133
	v_mov_b32_e32 v105, v133
	v_mov_b32_e32 v106, v133
	v_mov_b32_e32 v107, v133
	v_mov_b32_e32 v108, v133
	v_mov_b32_e32 v109, v133
	v_mov_b32_e32 v110, v133
	v_mov_b32_e32 v111, v133
	v_mov_b32_e32 v112, v133
	v_mov_b32_e32 v113, v133
	v_mov_b32_e32 v114, v133
	v_mov_b32_e32 v115, v133
	v_mov_b32_e32 v116, v133
	v_mov_b32_e32 v117, v133
	v_mov_b32_e32 v118, v133
	v_mov_b32_e32 v119, v133
	v_mov_b32_e32 v120, v133
	v_mov_b32_e32 v121, v133
	v_mov_b32_e32 v122, v133
	v_mov_b32_e32 v123, v133
	v_mov_b32_e32 v124, v133
	v_mov_b32_e32 v125, v133
	v_mov_b32_e32 v126, v133
	v_mov_b32_e32 v127, v133
	s_barrier

.LBB0_2750:
	s_lshl_b32 s3, s6, 5
	s_mov_b64 s[6:7], 0x80
	s_and_b32 s3, s3, 0x60
	s_add_i32 m0, s34, 0x18000
	v_lshl_add_u64 v[6:7], v[6:7], 0, s[6:7]
	s_lshl_b32 s1, s13, 13
	s_lshl_b32 s15, s3, 7
	global_load_lds_dwordx4 v[6:7], off
	v_lshl_add_u64 v[4:5], v[4:5], 0, s[6:7]
	s_add_i32 m0, s34, 0x1a000
	s_add_i32 s68, s34, 0x8000
	s_add_i32 s69, s34, 0xa000
	global_load_lds_dwordx4 v[4:5], off
	v_lshl_add_u64 v[0:1], v[0:1], 0, s[6:7]
	s_mov_b32 m0, s68
	s_add_u32 s16, s56, 0x10080
	global_load_lds_dwordx4 v[0:1], off
	v_lshl_add_u64 v[0:1], v[2:3], 0, s[6:7]
	s_mov_b32 m0, s69
	s_addc_u32 s17, s57, 0
	global_load_lds_dwordx4 v[0:1], off
	s_add_i32 m0, s34, 0x1c000
	v_lshl_add_u64 v[0:1], s[16:17], 0, v[134:135]
	global_load_lds_dwordx4 v[0:1], off
	v_lshl_add_u64 v[0:1], s[16:17], 0, v[138:139]
	s_add_i32 m0, s34, 0x1e000
	s_cmpk_lt_u32 s12, 0x100
	global_load_lds_dwordx4 v[0:1], off
	v_lshrrev_b32_e32 v1, 1, v8
	v_and_b32_e32 v1, 24, v1
	v_and_b32_e32 v0, 15, v8
	v_lshlrev_b32_e32 v2, 1, v1
	v_lshl_or_b32 v144, s13, 6, v0
	v_lshl_or_b32 v0, v0, 6, v2
	v_lshlrev_b32_e32 v2, 2, v8
	v_and_b32_e32 v2, 32, v2
	v_bitop3_b32 v3, v0, s1, v2 bitop3:0xde
	s_cselect_b64 s[12:13], -1, 0
	s_ashr_i32 s71, s97, 31
	s_ashr_i32 s1, s14, 31
	s_waitcnt vmcnt(6)
	s_barrier
	s_add_u32 s14, s14, s97
	v_bitop3_b32 v145, s15, v0, v2 bitop3:0xf6
	s_addc_u32 s15, s1, s71
	s_add_i32 s72, 0, 0x10000
	s_add_i32 s73, 0, 0x14000
	s_movk_i32 s70, 0x60
	v_or_b32_e32 v146, s3, v1
	v_add_u32_e32 v147, s72, v145
	v_add_u32_e32 v148, s73, v145
	v_add_u32_e32 v149, 0, v3
	s_add_i32 s74, s34, 0xc000
	s_add_i32 s75, s34, 0xe000
	s_mov_b64 s[16:17], 0x100
	s_mov_b64 s[18:19], 0x180
	s_movk_i32 s76, 0x81
	s_movk_i32 s77, 0x80
	s_movk_i32 s78, 0x71
	s_movk_i32 s79, 0x70
	s_movk_i32 s80, 0x61
	s_movk_i32 s81, 0x51
	s_movk_i32 s82, 0x50
	s_movk_i32 s83, 0xffe1
	s_movk_i32 s84, 0xffe0
	s_movk_i32 s85, 0xffd1
	s_movk_i32 s86, 0xffd0
	v_mov_b32_e32 v150, 0x80
	v_mov_b32_e32 v151, 0x400
	s_barrier
	s_branch .LBB0_2753

.LBB0_2972:
	s_add_u32 s35, s50, 0x112000
	s_addc_u32 s3, s51, 0
	v_writelane_b32 v255, s3, 56
	s_add_u32 s3, s50, 0x114000
	s_addc_u32 s86, s51, 0
	s_add_u32 s82, s50, 0x300000
	s_addc_u32 s83, s51, 0
	s_add_u32 s8, s50, 0x128020
	v_writelane_b32 v254, s3, 19
	s_addc_u32 s9, s51, 0
	v_writelane_b32 v254, s8, 31
	s_mov_b64 s[36:37], 0x80
	v_lshl_add_u64 v[6:7], v[6:7], 0, s[36:37]
	v_writelane_b32 v254, s9, 32
	s_add_u32 s8, s50, 0x170000
	s_addc_u32 s9, s51, 0
	s_and_b32 s34, s2, 3
	s_add_i32 m0, s78, 0x18000
	s_lshl_b32 s5, s34, 12
	global_load_lds_dwordx4 v[6:7], off
	v_lshl_add_u64 v[4:5], v[4:5], 0, s[36:37]
	s_add_i32 m0, s78, 0x1a000
	s_add_i32 s88, s78, 0x8000
	s_add_i32 s89, s78, 0xa000
	global_load_lds_dwordx4 v[4:5], off
	v_lshl_add_u64 v[2:3], v[2:3], 0, s[36:37]
	s_mov_b32 m0, s88
	s_add_u32 s2, s6, 0x80080
	global_load_lds_dwordx4 v[2:3], off
	v_lshl_add_u64 v[0:1], v[0:1], 0, s[36:37]
	s_mov_b32 m0, s89
	s_addc_u32 s3, s7, 0
	global_load_lds_dwordx4 v[0:1], off
	s_add_i32 m0, s78, 0x1c000
	v_lshl_add_u64 v[0:1], s[2:3], 0, v[110:111]
	global_load_lds_dwordx4 v[0:1], off
	v_lshl_add_u64 v[0:1], s[2:3], 0, v[114:115]
	s_add_i32 m0, s78, 0x1e000
	s_mul_i32 s2, s85, 0x1800
	global_load_lds_dwordx4 v[0:1], off
	v_and_b32_e32 v0, 15, v8
	v_and_b32_e32 v1, 48, v8
	v_lshl_or_b32 v0, v0, 6, v1
	v_lshlrev_b32_e32 v1, 2, v8
	v_and_b32_e32 v1, 32, v1
	v_bitop3_b32 v2, v0, s2, v1 bitop3:0xde
	v_bitop3_b32 v220, s5, v0, v1 bitop3:0xf6
	v_lshlrev_b32_e32 v0, 15, v9
	v_and_b32_e32 v0, 0xffff0000, v0
	v_writelane_b32 v254, s8, 27
	s_cmpk_lt_u32 s4, 0x100
	v_lshl_add_u32 v0, v10, 12, v0
	v_and_b32_e32 v1, 1, v9
	v_writelane_b32 v254, s9, 28
	s_cselect_b64 s[2:3], -1, 0
	v_lshl_or_b32 v0, v1, 6, v0
	v_writelane_b32 v254, s2, 21
	v_lshl_add_u32 v118, v11, 1, v0
	v_lshlrev_b32_e32 v0, 15, v12
	v_writelane_b32 v254, s3, 22
	s_ashr_i32 s2, s97, 31
	v_and_b32_e32 v0, 0xffff0000, v0
	s_waitcnt vmcnt(6)
	s_barrier
	v_writelane_b32 v255, s2, 2
	v_readlane_b32 s2, v254, 1
	v_lshl_add_u32 v0, v13, 12, v0
	v_and_b32_e32 v1, 1, v12
	s_ashr_i32 s2, s2, 31
	v_lshl_or_b32 v0, v1, 6, v0
	s_add_i32 s92, 0, 0x10000
	s_add_i32 s93, 0, 0x14000
	v_writelane_b32 v255, s2, 63
	v_mov_b32_e32 v119, v116
	v_lshl_add_u32 v120, v14, 1, v0
	v_mov_b32_e32 v121, v116
	v_mov_b64_e32 v[122:123], 0x100
	v_mov_b64_e32 v[124:125], 0xff
	v_add_u32_e32 v221, s92, v220
	v_add_u32_e32 v222, s93, v220
	v_add_u32_e32 v223, 0, v2
	v_mov_b32_e32 v3, 2.0
	s_mov_b32 s84, 0x3fb504f3
	s_mov_b64 s[56:57], 0x3000
	s_mov_b64 s[62:63], 0x4000
	v_mov_b32_e32 v224, 0xc0
	v_mov_b32_e32 v225, 0x1800
	s_mov_b32 s94, 0
	s_barrier
	s_branch .LBB0_2975

.LBB0_3053:
	v_readlane_b32 s68, v254, 3
	v_readlane_b32 s82, v254, 17
	v_readlane_b32 s83, v254, 18
	s_add_u32 s6, s82, 0x9800000
	s_addc_u32 s7, s83, 0
	s_lshl_b32 s8, s8, 5
	s_and_b32 s14, s8, 0x60
	s_mov_b64 s[8:9], 0x80
	v_readlane_b32 s69, v254, 4
	s_add_i32 m0, s53, 0x18000
	v_lshl_add_u64 v[6:7], v[6:7], 0, s[8:9]
	s_lshl_b32 s11, s10, 13
	s_lshl_b32 s15, s14, 7
	global_load_lds_dwordx4 v[6:7], off
	v_lshl_add_u64 v[4:5], v[4:5], 0, s[8:9]
	s_add_i32 m0, s53, 0x1a000
	s_add_i32 s68, s53, 0x8000
	s_add_i32 s69, s53, 0xa000
	global_load_lds_dwordx4 v[4:5], off
	v_lshl_add_u64 v[0:1], v[0:1], 0, s[8:9]
	s_mov_b32 m0, s68
	s_add_u32 s12, s56, 0x40080
	global_load_lds_dwordx4 v[0:1], off
	v_lshl_add_u64 v[0:1], v[2:3], 0, s[8:9]
	s_mov_b32 m0, s69
	s_addc_u32 s13, s57, 0
	global_load_lds_dwordx4 v[0:1], off
	s_add_i32 m0, s53, 0x1c000
	v_lshl_add_u64 v[0:1], s[12:13], 0, v[132:133]
	global_load_lds_dwordx4 v[0:1], off
	v_lshl_add_u64 v[0:1], s[12:13], 0, v[128:129]
	s_add_i32 m0, s53, 0x1e000
	v_readlane_b32 s71, v254, 6
	global_load_lds_dwordx4 v[0:1], off
	v_lshrrev_b32_e32 v1, 1, v8
	v_and_b32_e32 v1, 24, v1
	v_and_b32_e32 v0, 15, v8
	v_lshlrev_b32_e32 v2, 1, v1
	v_lshl_or_b32 v144, s10, 6, v0
	v_lshl_or_b32 v0, v0, 6, v2
	v_lshlrev_b32_e32 v2, 2, v8
	v_and_b32_e32 v2, 32, v2
	v_bitop3_b32 v3, v0, s11, v2 bitop3:0xde
	v_bitop3_b32 v145, s15, v0, v2 bitop3:0xf6
	v_lshlrev_b32_e32 v0, 14, v13
	v_and_b32_e32 v0, 0xffff8000, v0
	v_or_b32_e32 v146, s14, v1
	v_lshl_add_u32 v0, v12, 11, v0
	v_and_b32_e32 v1, 1, v13
	v_lshl_or_b32 v0, v1, 6, v0
	v_lshl_add_u32 v136, v14, 1, v0
	v_lshlrev_b32_e32 v0, 14, v9
	v_and_b32_e32 v0, 0xffff8000, v0
	v_readlane_b32 s72, v254, 7
	s_waitcnt vmcnt(6)
	s_barrier
	s_cmpk_lt_u32 s3, 0x100
	v_lshl_add_u32 v0, v10, 11, v0
	v_and_b32_e32 v1, 1, v9
	v_readlane_b32 s70, v254, 5
	v_readlane_b32 s73, v254, 8
	v_readlane_b32 s74, v254, 9
	v_readlane_b32 s75, v254, 10
	v_readlane_b32 s76, v254, 11
	v_readlane_b32 s77, v254, 12
	s_cselect_b64 s[10:11], -1, 0
	v_lshl_or_b32 v0, v1, 6, v0
	s_add_i32 s71, 0, 0x10000
	s_add_i32 s72, 0, 0x14000
	s_sext_i32_i8 s77, s2
	s_ashr_i32 s70, s97, 31
	v_mov_b32_e32 v137, v133
	v_lshl_add_u32 v138, v11, 1, v0
	v_mov_b32_e32 v139, v133
	v_mov_b64_e32 v[140:141], 0x300
	v_mov_b64_e32 v[142:143], 0x2ff
	v_add_u32_e32 v147, s71, v145
	v_add_u32_e32 v148, s72, v145
	v_add_u32_e32 v149, 0, v3
	s_mov_b64 s[12:13], 0x100000
	s_mov_b32 s73, 0x100000
	s_mov_b64 s[14:15], 0x120000
	s_mov_b32 s74, 0x120000
	s_mov_b64 s[16:17], 0x140000
	s_mov_b32 s75, 0x140000
	s_mov_b64 s[18:19], 0x160000
	s_mov_b32 s76, 0x160000
	v_readlane_b32 s78, v254, 13
	v_readlane_b32 s79, v254, 14
	v_readlane_b32 s80, v254, 15
	v_readlane_b32 s81, v254, 16
	s_barrier
	s_branch .LBB0_3056

.LBB0_3113:
	v_readlane_b32 s68, v254, 3
	v_readlane_b32 s76, v254, 11
	v_readlane_b32 s77, v254, 12
	v_readlane_b32 s78, v254, 13
	v_readlane_b32 s79, v254, 14
	v_readlane_b32 s80, v254, 15
	v_readlane_b32 s81, v254, 16
	v_readlane_b32 s82, v254, 17
	v_readlane_b32 s83, v254, 18
	s_mov_b64 s[20:21], s[76:77]
	s_mov_b64 s[26:27], s[82:83]
	s_add_u32 s65, s26, 0x117000
	s_addc_u32 s66, s27, 0
	s_add_u32 s12, s26, 0x170000
	s_mov_b64 s[14:15], 0x80
	v_readlane_b32 s69, v254, 4
	s_addc_u32 s13, s27, 0
	s_and_b32 s67, s0, 3
	s_add_i32 m0, s60, 0x18000
	v_lshl_add_u64 v[8:9], v[8:9], 0, s[14:15]
	s_lshl_b32 s2, s67, 12
	global_load_lds_dwordx4 v[8:9], off
	v_lshl_add_u64 v[6:7], v[6:7], 0, s[14:15]
	s_add_i32 m0, s60, 0x1a000
	s_add_i32 s68, s60, 0x8000
	s_add_i32 s69, s60, 0xa000
	global_load_lds_dwordx4 v[6:7], off
	v_lshl_add_u64 v[0:1], v[0:1], 0, s[14:15]
	s_mov_b32 m0, s68
	s_add_u32 s0, s6, 0x100080
	global_load_lds_dwordx4 v[0:1], off
	v_lshl_add_u64 v[0:1], v[4:5], 0, s[14:15]
	s_mov_b32 m0, s69
	s_addc_u32 s1, s7, 0
	global_load_lds_dwordx4 v[0:1], off
	s_add_i32 m0, s60, 0x1c000
	v_lshl_add_u64 v[0:1], s[0:1], 0, v[162:163]
	global_load_lds_dwordx4 v[0:1], off
	v_lshl_add_u64 v[0:1], s[0:1], 0, v[166:167]
	s_add_i32 m0, s60, 0x1e000
	s_mul_i32 s0, s56, 0x1800
	global_load_lds_dwordx4 v[0:1], off
	v_and_b32_e32 v0, 15, v3
	v_and_b32_e32 v1, 48, v3
	v_lshl_or_b32 v0, v0, 6, v1
	v_lshlrev_b32_e32 v1, 2, v3
	v_and_b32_e32 v1, 32, v1
	v_bitop3_b32 v3, v0, s0, v1 bitop3:0xde
	v_bitop3_b32 v226, s2, v0, v1 bitop3:0xf6
	v_lshlrev_b32_e32 v0, 16, v10
	v_and_b32_e32 v0, 0xfffe0000, v0
	v_lshl_add_u32 v0, v11, 13, v0
	v_and_b32_e32 v1, 1, v10
	v_lshl_or_b32 v0, v1, 6, v0
	v_lshl_add_u32 v168, v12, 1, v0
	v_lshlrev_b32_e32 v0, 16, v13
	v_and_b32_e32 v0, 0xfffe0000, v0
	v_readlane_b32 s72, v254, 7
	v_readlane_b32 s73, v254, 8
	s_waitcnt vmcnt(6)
	s_barrier
	s_cmpk_lt_u32 s8, 0x100
	v_lshl_add_u32 v0, v14, 13, v0
	v_and_b32_e32 v1, 1, v13
	v_readlane_b32 s70, v254, 5
	v_readlane_b32 s71, v254, 6
	v_readlane_b32 s74, v254, 9
	v_readlane_b32 s75, v254, 10
	s_mov_b64 s[22:23], s[78:79]
	s_mov_b64 s[24:25], s[80:81]
	s_cselect_b64 s[16:17], -1, 0
	v_lshl_or_b32 v0, v1, 6, v0
	s_add_i32 s72, 0, 0x10000
	s_add_i32 s73, 0, 0x14000
	s_ashr_i32 s70, s97, 31
	s_ashr_i32 s71, s36, 31
	v_mov_b32_e32 v169, v2
	v_lshl_add_u32 v170, v15, 1, v0
	v_mov_b32_e32 v171, v2
	v_mov_b64_e32 v[172:173], 0x100
	v_mov_b64_e32 v[174:175], 0xff
	v_add_u32_e32 v227, s72, v226
	v_add_u32_e32 v228, s73, v226
	v_add_u32_e32 v229, 0, v3
	s_mov_b32 s18, 0x3fb504f3
	v_mov_b32_e32 v230, 0x40400000
	s_mov_b64 s[20:21], 0x1800
	s_mov_b64 s[22:23], 0x3000
	s_mov_b64 s[24:25], 0x4800
	s_mov_b32 s74, 0x40400000
	v_mov_b32_e32 v231, 0xc0
	v_mov_b32_e32 v232, 0x1800
	s_mov_b32 s75, 0
	s_barrier
	s_branch .LBB0_3116
